# conversion split plus attention unit prologue: tile 1 requested with tile 0, tile 2 left in flight into the loop
# baseline (speedup 1.0000x reference)
.LBB0_752:
	s_cmp_lg_u32 s84, s94
	s_mov_b64 s[0:1], -1
	s_cbranch_scc0 .LBB0_770
	s_lshl_b32 s0, s46, 3
	s_and_b32 s0, s0, -16
	s_bitcmp0_b32 s46, 0
	s_cselect_b32 s1, s96, s22
	s_or_b32 s8, s1, s0
	s_lshl_b32 s0, s8, 7
	s_ashr_i32 s1, s0, 31
	s_waitcnt lgkmcnt(0)
	s_add_u32 s12, s56, s0
	s_addc_u32 s13, s57, s1
	s_lshl_b64 s[0:1], s[12:13], 10
	v_mov_b32_e32 v44, v0
	s_add_u32 s0, s92, s0
	s_addc_u32 s1, s18, s1
	v_and_b32_e32 v156, 31, v44
	v_mov_b32_e32 v163, v162
	v_lshlrev_b32_e32 v2, 10, v156
	v_mov_b32_e32 v164, v162
	v_mov_b32_e32 v165, v162
	v_mov_b32_e32 v166, v162
	v_mov_b32_e32 v167, v162
	v_mov_b32_e32 v168, v162
	v_mov_b32_e32 v169, v162
	s_waitcnt vmcnt(0)
	v_mov_b64_e32 v[124:125], v[162:163]
	v_lshl_add_u64 v[4:5], s[0:1], 0, v[2:3]
	v_and_b32_e32 v38, 32, v44
	v_mov_b32_e32 v39, v3
	v_mov_b64_e32 v[126:127], v[164:165]
	v_mov_b64_e32 v[128:129], v[166:167]
	v_mov_b64_e32 v[130:131], v[168:169]
	v_lshl_add_u64 v[4:5], v[4:5], 0, v[38:39]
	v_lshlrev_b32_e32 v36, 4, v44
	global_load_dwordx4 v[136:139], v[4:5], off offset:16
	global_load_dwordx4 v[132:135], v[4:5], off
	v_ashrrev_i32_e32 v1, 3, v44
	v_and_b32_e32 v4, 0x70, v36
	v_lshl_or_b32 v2, v1, 10, v4
	s_movk_i32 s0, 0x90
	v_mad_u64_u32 v[158:159], s[0:1], v1, s0, v[4:5]
	v_and_b32_e32 v4, 48, v36
	global_load_dwordx4 v[140:143], v2, s[60:61]
	global_load_dwordx4 v[144:147], v36, s[64:65]
	global_load_dwordx4 v[148:151], v2, s[66:67]
	global_load_dwordx4 v[152:155], v36, s[68:69]
	v_lshrrev_b32_e32 v1, 2, v44
	v_mul_u32_u24_e32 v5, 0x90, v156
	v_mad_u64_u32 v[160:161], s[0:1], v1, s20, v[4:5]
	v_add3_u32 v157, s87, v5, v38
	v_add_u32_e32 v39, 0, v158
	v_add_u32_e32 v45, 0, v160
	s_waitcnt vmcnt(2)
	s_cmp_lt_i32 s46, 0
	s_cselect_b64 vcc, -1, 0
	v_readfirstlane_b32 s2, v44
	v_mov_b32_e32 v37, v3
	ds_write_b128 v39, v[140:143]
	ds_write_b128 v45, v[144:147] offset:9216
	s_waitcnt lgkmcnt(0)
	s_barrier
	ds_read_b128 v[4:7], v157
	ds_read_b128 v[8:11], v157 offset:16
	ds_read_b128 v[12:15], v157 offset:4608
	ds_read_b128 v[16:19], v157 offset:4624
	s_waitcnt lgkmcnt(2)
	v_mfma_f32_32x32x64_f8f6f4 v[20:35], v[4:11], v[132:139], 0
	s_waitcnt lgkmcnt(0)
	v_mfma_f32_32x32x64_f8f6f4 v[4:19], v[12:19], v[132:139], 0
	s_nop 15
	s_nop 1
	v_max_f32_e32 v1, v21, v21
	v_max_f32_e32 v40, v20, v20
	v_max_f32_e32 v1, v40, v1
	v_max3_f32 v1, v1, v22, v23
	v_max3_f32 v1, v1, v24, v25
	v_max3_f32 v1, v1, v26, v27
	v_max3_f32 v1, v1, v28, v29
	v_max3_f32 v1, v1, v30, v31
	v_max3_f32 v1, v1, v32, v33
	v_max3_f32 v1, v1, v34, v35
	v_max3_f32 v1, v1, v4, v5
	v_max3_f32 v1, v1, v6, v7
	v_max3_f32 v1, v1, v8, v9
	v_max3_f32 v1, v1, v10, v11
	v_max3_f32 v1, v1, v12, v13
	v_max3_f32 v1, v1, v14, v15
	v_max3_f32 v1, v1, v16, v17
	v_max3_f32 v1, v1, v18, v19
	v_mov_b32_e32 v40, v1
	s_nop 1
	v_permlane32_swap_b32_e32 v1, v40
	v_max_f32_e32 v40, v40, v40
	v_max_f32_e32 v1, v1, v1
	v_max_f32_e32 v1, v1, v40
	v_cndmask_b32_e32 v1, v1, v197, vcc
	v_add_f32_e32 v40, 0x7149f2ca, v1
	v_cmp_ge_f32_e64 s[6:7], s21, v40
	s_cmp_lg_u64 s[6:7], exec
	v_max_f32_e32 v1, 0xf149f2ca, v1
	s_cselect_b64 s[6:7], -1, 0
	v_cndmask_b32_e64 v172, v197, v1, s[6:7]
	v_fmamk_f32 v1, v172, 0xba38aa3b, v194
	v_mul_f32_e32 v1, 0x4b000000, v1
	v_cndmask_b32_e64 v40, v193, 0, vcc
	v_cndmask_b32_e32 v42, v1, v197, vcc
	v_pk_fma_f32 v[4:5], v[4:5], v[40:41], v[42:43] op_sel_hi:[1,0,0]
	v_pk_fma_f32 v[6:7], v[6:7], v[40:41], v[42:43] op_sel_hi:[1,0,0]
	v_pk_fma_f32 v[8:9], v[8:9], v[40:41], v[42:43] op_sel_hi:[1,0,0]
	v_pk_fma_f32 v[10:11], v[10:11], v[40:41], v[42:43] op_sel_hi:[1,0,0]
	v_cvt_u32_f32 v176, v4
	v_cvt_u32_f32 v177, v5
	v_cvt_u32_f32 v99, v6
	v_cvt_u32_f32 v173, v7
	v_cvt_u32_f32 v178, v8
	v_cvt_u32_f32 v179, v9
	s_nop 0
	v_cvt_u32_f32 v174, v10
	v_cvt_u32_f32 v175, v11
	s_cmp_lt_i32 s8, 1
	s_cselect_b64 s[0:1], -1, 0
	s_and_b64 vcc, exec, s[0:1]
	v_pk_fma_f32 v[20:21], v[20:21], v[40:41], v[42:43] op_sel_hi:[1,0,0]
	v_pk_fma_f32 v[22:23], v[22:23], v[40:41], v[42:43] op_sel_hi:[1,0,0]
	v_pk_fma_f32 v[24:25], v[24:25], v[40:41], v[42:43] op_sel_hi:[1,0,0]
	v_pk_fma_f32 v[26:27], v[26:27], v[40:41], v[42:43] op_sel_hi:[1,0,0]
	v_pk_fma_f32 v[28:29], v[28:29], v[40:41], v[42:43] op_sel_hi:[1,0,0]
	v_pk_fma_f32 v[30:31], v[30:31], v[40:41], v[42:43] op_sel_hi:[1,0,0]
	v_pk_fma_f32 v[32:33], v[32:33], v[40:41], v[42:43] op_sel_hi:[1,0,0]
	v_pk_fma_f32 v[34:35], v[34:35], v[40:41], v[42:43] op_sel_hi:[1,0,0]
	v_cvt_u32_f32 v96, v20
	v_cvt_u32_f32 v1, v21
	v_cvt_u32_f32 v98, v22
	v_cvt_u32_f32 v97, v23
	v_cvt_u32_f32 v88, v24
	v_cvt_u32_f32 v89, v25
	v_cvt_u32_f32 v84, v26
	v_cvt_u32_f32 v85, v27
	v_cvt_u32_f32 v90, v28
	v_cvt_u32_f32 v91, v29
	v_cvt_u32_f32 v86, v30
	v_cvt_u32_f32 v87, v31
	v_cvt_u32_f32 v92, v32
	v_cvt_u32_f32 v93, v33
	s_nop 0
	v_cvt_u32_f32 v94, v34
	v_cvt_u32_f32 v95, v35
	s_cbranch_vccnz .Lpro_skip
	v_lshl_add_u64 v[20:21], s[70:71], 0, v[2:3]
	v_lshl_add_u64 v[22:23], s[72:73], 0, v[36:37]
	global_load_dwordx4 v[140:143], v[20:21], off
	global_load_dwordx4 v[144:147], v[22:23], off
.LBB0_755:
	s_waitcnt vmcnt(2)
	v_mov_b32_e32 v41, v40
	v_mov_b32_e32 v43, v42
	v_pk_fma_f32 v[100:101], v[12:13], v[40:41], v[42:43]
	v_pk_fma_f32 v[102:103], v[14:15], v[40:41], v[42:43]
	v_pk_fma_f32 v[120:121], v[16:17], v[40:41], v[42:43]
	v_pk_fma_f32 v[122:123], v[18:19], v[40:41], v[42:43]
	s_andn2_b64 vcc, exec, s[0:1]
	s_mov_b64 s[0:1], -1
	ds_write_b128 v39, v[148:151] offset:19456
	ds_write_b128 v45, v[152:155] offset:28672
	s_waitcnt lgkmcnt(0)
	s_barrier
	s_cbranch_vccnz .LBB0_757
	s_mov_b64 s[0:1], 0
